# tail split, specialised half-unit loops placed out of line (full-unit path: one compare + untaken branch)
# speedup vs baseline: 1.0019x; 1.0019x over previous
.LBB0_1831:
	v_lshl_add_u64 v[150:151], v[0:1], 0, s[20:21]
	v_mov_b32_e32 v0, 0
	v_lshl_add_u64 v[148:149], v[2:3], 0, s[18:19]
	s_mov_b32 s44, -2
	v_mov_b32_e32 v1, v0
	v_mov_b32_e32 v2, v0
	v_mov_b32_e32 v3, v0
	v_mov_b32_e32 v4, v0
	v_mov_b32_e32 v5, v0
	v_mov_b32_e32 v6, v0
	v_mov_b32_e32 v7, v0
	v_mov_b32_e32 v8, v0
	v_mov_b32_e32 v9, v0
	v_mov_b32_e32 v10, v0
	v_mov_b32_e32 v11, v0
	v_mov_b32_e32 v16, v0
	v_mov_b32_e32 v17, v0
	v_mov_b32_e32 v18, v0
	v_mov_b32_e32 v19, v0
	v_mov_b32_e32 v24, v0
	v_mov_b32_e32 v25, v0
	v_mov_b32_e32 v26, v0
	v_mov_b32_e32 v27, v0
	v_mov_b32_e32 v32, v0
	v_mov_b32_e32 v33, v0
	v_mov_b32_e32 v34, v0
	v_mov_b32_e32 v35, v0
	v_mov_b32_e32 v40, v0
	v_mov_b32_e32 v41, v0
	v_mov_b32_e32 v42, v0
	v_mov_b32_e32 v43, v0
	v_mov_b32_e32 v48, v0
	v_mov_b32_e32 v49, v0
	v_mov_b32_e32 v50, v0
	v_mov_b32_e32 v51, v0
	v_mov_b32_e32 v12, v0
	v_mov_b32_e32 v13, v0
	v_mov_b32_e32 v14, v0
	v_mov_b32_e32 v15, v0
	v_mov_b32_e32 v20, v0
	v_mov_b32_e32 v21, v0
	v_mov_b32_e32 v22, v0
	v_mov_b32_e32 v23, v0
	v_mov_b32_e32 v28, v0
	v_mov_b32_e32 v29, v0
	v_mov_b32_e32 v30, v0
	v_mov_b32_e32 v31, v0
	v_mov_b32_e32 v36, v0
	v_mov_b32_e32 v37, v0
	v_mov_b32_e32 v38, v0
	v_mov_b32_e32 v39, v0
	v_mov_b32_e32 v44, v0
	v_mov_b32_e32 v45, v0
	v_mov_b32_e32 v46, v0
	v_mov_b32_e32 v47, v0
	v_mov_b32_e32 v52, v0
	v_mov_b32_e32 v53, v0
	v_mov_b32_e32 v54, v0
	v_mov_b32_e32 v55, v0
	v_mov_b32_e32 v56, v0
	v_mov_b32_e32 v57, v0
	v_mov_b32_e32 v58, v0
	v_mov_b32_e32 v59, v0
	v_mov_b32_e32 v60, v0
	v_mov_b32_e32 v61, v0
	v_mov_b32_e32 v62, v0
	v_mov_b32_e32 v63, v0
	v_mov_b32_e32 v64, v0
	v_mov_b32_e32 v65, v0
	v_mov_b32_e32 v66, v0
	v_mov_b32_e32 v67, v0
	v_mov_b32_e32 v68, v0
	v_mov_b32_e32 v69, v0
	v_mov_b32_e32 v70, v0
	v_mov_b32_e32 v71, v0
	v_mov_b32_e32 v72, v0
	v_mov_b32_e32 v73, v0
	v_mov_b32_e32 v74, v0
	v_mov_b32_e32 v75, v0
	v_mov_b32_e32 v80, v0
	v_mov_b32_e32 v81, v0
	v_mov_b32_e32 v82, v0
	v_mov_b32_e32 v83, v0
	v_mov_b32_e32 v88, v0
	v_mov_b32_e32 v89, v0
	v_mov_b32_e32 v90, v0
	v_mov_b32_e32 v91, v0
	v_mov_b32_e32 v96, v0
	v_mov_b32_e32 v97, v0
	v_mov_b32_e32 v98, v0
	v_mov_b32_e32 v99, v0
	v_mov_b32_e32 v104, v0
	v_mov_b32_e32 v105, v0
	v_mov_b32_e32 v106, v0
	v_mov_b32_e32 v107, v0
	v_mov_b32_e32 v112, v0
	v_mov_b32_e32 v113, v0
	v_mov_b32_e32 v114, v0
	v_mov_b32_e32 v115, v0
	v_mov_b32_e32 v76, v0
	v_mov_b32_e32 v77, v0
	v_mov_b32_e32 v78, v0
	v_mov_b32_e32 v79, v0
	v_mov_b32_e32 v84, v0
	v_mov_b32_e32 v85, v0
	v_mov_b32_e32 v86, v0
	v_mov_b32_e32 v87, v0
	v_mov_b32_e32 v92, v0
	v_mov_b32_e32 v93, v0
	v_mov_b32_e32 v94, v0
	v_mov_b32_e32 v95, v0
	v_mov_b32_e32 v100, v0
	v_mov_b32_e32 v101, v0
	v_mov_b32_e32 v102, v0
	v_mov_b32_e32 v103, v0
	v_mov_b32_e32 v108, v0
	v_mov_b32_e32 v109, v0
	v_mov_b32_e32 v110, v0
	v_mov_b32_e32 v111, v0
	v_mov_b32_e32 v116, v0
	v_mov_b32_e32 v117, v0
	v_mov_b32_e32 v118, v0
	v_mov_b32_e32 v119, v0
	v_mov_b32_e32 v120, v0
	v_mov_b32_e32 v121, v0
	v_mov_b32_e32 v122, v0
	v_mov_b32_e32 v123, v0
	v_mov_b32_e32 v124, v0
	v_mov_b32_e32 v125, v0
	v_mov_b32_e32 v126, v0
	v_mov_b32_e32 v127, v0
	s_cmp_eq_u32 s90, 3
	s_cbranch_scc0 .Lts_b_sel

.Lts_b_x:
	v_add_u32_e32 v140, v140, v154
	v_ashrrev_i32_e32 v141, 31, v140
	v_add_u32_e32 v148, s74, v156
	v_lshlrev_b64 v[140:141], 12, v[140:141]
	v_ashrrev_i32_e32 v149, 31, v148
	v_lshl_add_u64 v[140:141], s[14:15], 0, v[140:141]
	v_add_f32_e32 v124, 0, v124
	v_add_f32_e32 v125, 0, v125
	v_lshl_add_u64 v[140:141], v[148:149], 1, v[140:141]
	v_cvt_pk_bf16_f32 v124, v124, v125
	v_add_f32_e32 v125, 0, v126
	v_add_f32_e32 v120, 0, v120
	v_add_f32_e32 v121, 0, v121
	v_add_f32_e32 v126, 0, v127
	v_cvt_pk_bf16_f32 v125, v125, v126
	s_and_saveexec_b64 s[98:99], s[86:87]
	global_store_dwordx2 v[140:141], v[124:125], off
	s_mov_b64 exec, s[98:99]
	v_cvt_pk_bf16_f32 v120, v120, v121
	v_add_f32_e32 v121, 0, v122
	v_add_f32_e32 v112, 0, v112
	v_add_f32_e32 v113, 0, v113
	v_add_f32_e32 v122, 0, v123
	v_cvt_pk_bf16_f32 v121, v121, v122
	s_and_saveexec_b64 s[98:99], s[86:87]
	global_store_dwordx2 v[140:141], v[120:121], off offset:32
	s_mov_b64 exec, s[98:99]
	v_cvt_pk_bf16_f32 v112, v112, v113
	v_add_f32_e32 v113, 0, v114
	v_add_f32_e32 v104, 0, v104
	v_add_f32_e32 v105, 0, v105
	v_add_f32_e32 v114, 0, v115
	v_cvt_pk_bf16_f32 v113, v113, v114
	s_and_saveexec_b64 s[98:99], s[86:87]
	global_store_dwordx2 v[140:141], v[112:113], off offset:256
	s_mov_b64 exec, s[98:99]
	v_cvt_pk_bf16_f32 v104, v104, v105
	v_add_f32_e32 v105, 0, v106
	v_add_f32_e32 v106, 0, v107
	v_cvt_pk_bf16_f32 v105, v105, v106
	v_add_f32_e32 v106, 0, v116
	v_add_f32_e32 v107, 0, v117
	s_and_saveexec_b64 s[98:99], s[86:87]
	global_store_dwordx2 v[140:141], v[104:105], off offset:288
	s_mov_b64 exec, s[98:99]
	v_cvt_pk_bf16_f32 v106, v106, v107
	v_add_f32_e32 v107, 0, v118
	v_add_f32_e32 v112, 0, v119
	v_cvt_pk_bf16_f32 v107, v107, v112
	v_add_co_u32_e32 v112, vcc, s58, v140
	v_lshl_add_u64 v[104:105], v[140:141], 0, s[24:25]
	s_nop 0
	v_addc_co_u32_e32 v113, vcc, 0, v141, vcc
	s_and_saveexec_b64 s[98:99], s[86:87]
	global_store_dwordx2 v[112:113], v[106:107], off
	s_mov_b64 exec, s[98:99]
	v_add_f32_e32 v106, 0, v108
	v_add_f32_e32 v107, 0, v109
	v_cvt_pk_bf16_f32 v106, v106, v107
	v_add_f32_e32 v107, 0, v110
	v_add_f32_e32 v96, 0, v96
	v_add_f32_e32 v97, 0, v97
	v_add_f32_e32 v108, 0, v111
	v_cvt_pk_bf16_f32 v107, v107, v108
	s_and_saveexec_b64 s[98:99], s[86:87]
	global_store_dwordx2 v[104:105], v[106:107], off offset:32
	s_mov_b64 exec, s[98:99]
	v_cvt_pk_bf16_f32 v96, v96, v97
	v_add_f32_e32 v97, 0, v98
	v_add_f32_e32 v88, 0, v88
	v_add_f32_e32 v89, 0, v89
	v_add_f32_e32 v98, 0, v99
	v_cvt_pk_bf16_f32 v97, v97, v98
	s_and_saveexec_b64 s[98:99], s[86:87]
	global_store_dwordx2 v[104:105], v[96:97], off offset:256
	s_mov_b64 exec, s[98:99]
	v_cvt_pk_bf16_f32 v88, v88, v89
	v_add_f32_e32 v89, 0, v90
	v_add_f32_e32 v90, 0, v91
	v_cvt_pk_bf16_f32 v89, v89, v90
	v_add_f32_e32 v90, 0, v100
	v_add_f32_e32 v91, 0, v101
	s_and_saveexec_b64 s[98:99], s[86:87]
	global_store_dwordx2 v[104:105], v[88:89], off offset:288
	s_mov_b64 exec, s[98:99]
	v_cvt_pk_bf16_f32 v90, v90, v91
	v_add_f32_e32 v91, 0, v102
	v_add_f32_e32 v96, 0, v103
	v_cvt_pk_bf16_f32 v91, v91, v96
	v_add_co_u32_e32 v96, vcc, s67, v140
	v_lshl_add_u64 v[88:89], v[140:141], 0, s[26:27]
	s_nop 0
	v_addc_co_u32_e32 v97, vcc, 0, v141, vcc
	s_and_saveexec_b64 s[98:99], s[86:87]
	global_store_dwordx2 v[96:97], v[90:91], off
	s_mov_b64 exec, s[98:99]
	v_add_f32_e32 v90, 0, v92
	v_add_f32_e32 v91, 0, v93
	v_cvt_pk_bf16_f32 v90, v90, v91
	v_add_f32_e32 v91, 0, v94
	v_add_f32_e32 v80, 0, v80
	v_add_f32_e32 v81, 0, v81
	v_add_f32_e32 v92, 0, v95
	v_cvt_pk_bf16_f32 v91, v91, v92
	s_and_saveexec_b64 s[98:99], s[86:87]
	global_store_dwordx2 v[88:89], v[90:91], off offset:32
	s_mov_b64 exec, s[98:99]
	v_cvt_pk_bf16_f32 v80, v80, v81
	v_add_f32_e32 v81, 0, v82
	v_add_f32_e32 v72, 0, v72
	v_add_f32_e32 v73, 0, v73
	v_add_f32_e32 v82, 0, v83
	v_cvt_pk_bf16_f32 v81, v81, v82
	s_and_saveexec_b64 s[98:99], s[86:87]
	global_store_dwordx2 v[88:89], v[80:81], off offset:256
	s_mov_b64 exec, s[98:99]
	v_cvt_pk_bf16_f32 v72, v72, v73
	v_add_f32_e32 v73, 0, v74
	v_add_f32_e32 v74, 0, v75
	v_cvt_pk_bf16_f32 v73, v73, v74
	v_add_f32_e32 v74, 0, v84
	v_add_f32_e32 v75, 0, v85
	s_and_saveexec_b64 s[98:99], s[86:87]
	global_store_dwordx2 v[88:89], v[72:73], off offset:288
	s_mov_b64 exec, s[98:99]
	v_cvt_pk_bf16_f32 v74, v74, v75
	v_add_f32_e32 v75, 0, v86
	v_add_f32_e32 v80, 0, v87
	v_cvt_pk_bf16_f32 v75, v75, v80
	v_add_co_u32_e32 v80, vcc, s68, v140
	v_lshl_add_u64 v[72:73], v[140:141], 0, s[28:29]
	s_nop 0
	v_addc_co_u32_e32 v81, vcc, 0, v141, vcc
	s_and_saveexec_b64 s[98:99], s[86:87]
	global_store_dwordx2 v[80:81], v[74:75], off
	s_mov_b64 exec, s[98:99]
	v_add_f32_e32 v74, 0, v76
	v_add_f32_e32 v75, 0, v77
	v_cvt_pk_bf16_f32 v74, v74, v75
	v_add_f32_e32 v75, 0, v78
	v_add_f32_e32 v68, 0, v68
	v_add_f32_e32 v69, 0, v69
	v_add_f32_e32 v76, 0, v79
	v_cvt_pk_bf16_f32 v75, v75, v76
	s_and_saveexec_b64 s[98:99], s[86:87]
	global_store_dwordx2 v[72:73], v[74:75], off offset:32
	s_mov_b64 exec, s[98:99]
	v_cvt_pk_bf16_f32 v68, v68, v69
	v_add_f32_e32 v69, 0, v70
	v_add_f32_e32 v64, 0, v64
	v_add_f32_e32 v65, 0, v65
	v_add_f32_e32 v70, 0, v71
	v_cvt_pk_bf16_f32 v69, v69, v70
	s_and_saveexec_b64 s[98:99], s[86:87]
	global_store_dwordx2 v[72:73], v[68:69], off offset:256
	s_mov_b64 exec, s[98:99]
	v_cvt_pk_bf16_f32 v64, v64, v65
	v_add_f32_e32 v65, 0, v66
	v_add_f32_e32 v60, 0, v60
	v_add_f32_e32 v61, 0, v61
	v_add_f32_e32 v66, 0, v67
	v_cvt_pk_bf16_f32 v65, v65, v66
	s_and_saveexec_b64 s[98:99], s[86:87]
	global_store_dwordx2 v[72:73], v[64:65], off offset:288
	s_mov_b64 exec, s[98:99]
	v_cvt_pk_bf16_f32 v60, v60, v61
	v_add_f32_e32 v61, 0, v62
	v_add_f32_e32 v62, 0, v63
	v_cvt_pk_bf16_f32 v61, v61, v62
	v_add_co_u32_e32 v62, vcc, s69, v140
	v_add_f32_e32 v56, 0, v56
	s_nop 0
	v_addc_co_u32_e32 v63, vcc, 0, v141, vcc
	v_add_f32_e32 v57, 0, v57
	v_lshl_add_u64 v[64:65], v[140:141], 0, s[30:31]
	s_and_saveexec_b64 s[98:99], s[88:89]
	global_store_dwordx2 v[62:63], v[60:61], off
	s_mov_b64 exec, s[98:99]
	v_cvt_pk_bf16_f32 v56, v56, v57
	v_add_f32_e32 v57, 0, v58
	v_add_f32_e32 v48, 0, v48
	v_add_f32_e32 v49, 0, v49
	v_add_f32_e32 v58, 0, v59
	v_cvt_pk_bf16_f32 v57, v57, v58
	s_and_saveexec_b64 s[98:99], s[88:89]
	global_store_dwordx2 v[64:65], v[56:57], off offset:32
	s_mov_b64 exec, s[98:99]
	v_cvt_pk_bf16_f32 v48, v48, v49
	v_add_f32_e32 v49, 0, v50
	v_add_f32_e32 v40, 0, v40
	v_add_f32_e32 v41, 0, v41
	v_add_f32_e32 v50, 0, v51
	v_cvt_pk_bf16_f32 v49, v49, v50
	s_and_saveexec_b64 s[98:99], s[88:89]
	global_store_dwordx2 v[64:65], v[48:49], off offset:256
	s_mov_b64 exec, s[98:99]
	v_cvt_pk_bf16_f32 v40, v40, v41
	v_add_f32_e32 v41, 0, v42
	v_add_f32_e32 v42, 0, v43
	v_cvt_pk_bf16_f32 v41, v41, v42
	v_add_f32_e32 v42, 0, v52
	v_add_f32_e32 v43, 0, v53
	s_and_saveexec_b64 s[98:99], s[88:89]
	global_store_dwordx2 v[64:65], v[40:41], off offset:288
	s_mov_b64 exec, s[98:99]
	v_cvt_pk_bf16_f32 v42, v42, v43
	v_add_f32_e32 v43, 0, v54
	v_add_f32_e32 v48, 0, v55
	v_cvt_pk_bf16_f32 v43, v43, v48
	v_add_co_u32_e32 v48, vcc, s70, v140
	v_lshl_add_u64 v[40:41], v[140:141], 0, s[34:35]
	s_nop 0
	v_addc_co_u32_e32 v49, vcc, 0, v141, vcc
	s_and_saveexec_b64 s[98:99], s[88:89]
	global_store_dwordx2 v[48:49], v[42:43], off
	s_mov_b64 exec, s[98:99]
	v_add_f32_e32 v42, 0, v44
	v_add_f32_e32 v43, 0, v45
	v_cvt_pk_bf16_f32 v42, v42, v43
	v_add_f32_e32 v43, 0, v46
	v_add_f32_e32 v32, 0, v32
	v_add_f32_e32 v33, 0, v33
	v_add_f32_e32 v44, 0, v47
	v_cvt_pk_bf16_f32 v43, v43, v44
	s_and_saveexec_b64 s[98:99], s[88:89]
	global_store_dwordx2 v[40:41], v[42:43], off offset:32
	s_mov_b64 exec, s[98:99]
	v_cvt_pk_bf16_f32 v32, v32, v33
	v_add_f32_e32 v33, 0, v34
	v_add_f32_e32 v24, 0, v24
	v_add_f32_e32 v25, 0, v25
	v_add_f32_e32 v34, 0, v35
	v_cvt_pk_bf16_f32 v33, v33, v34
	s_and_saveexec_b64 s[98:99], s[88:89]
	global_store_dwordx2 v[40:41], v[32:33], off offset:256
	s_mov_b64 exec, s[98:99]
	v_cvt_pk_bf16_f32 v24, v24, v25
	v_add_f32_e32 v25, 0, v26
	v_add_f32_e32 v26, 0, v27
	v_cvt_pk_bf16_f32 v25, v25, v26
	v_add_f32_e32 v26, 0, v36
	v_add_f32_e32 v27, 0, v37
	s_and_saveexec_b64 s[98:99], s[88:89]
	global_store_dwordx2 v[40:41], v[24:25], off offset:288
	s_mov_b64 exec, s[98:99]
	v_cvt_pk_bf16_f32 v26, v26, v27
	v_add_f32_e32 v27, 0, v38
	v_add_f32_e32 v32, 0, v39
	v_cvt_pk_bf16_f32 v27, v27, v32
	v_add_co_u32_e32 v32, vcc, s71, v140
	v_lshl_add_u64 v[24:25], v[140:141], 0, s[36:37]
	s_nop 0
	v_addc_co_u32_e32 v33, vcc, 0, v141, vcc
	s_and_saveexec_b64 s[98:99], s[88:89]
	global_store_dwordx2 v[32:33], v[26:27], off
	s_mov_b64 exec, s[98:99]
	v_add_f32_e32 v26, 0, v28
	v_add_f32_e32 v27, 0, v29
	v_cvt_pk_bf16_f32 v26, v26, v27
	v_add_f32_e32 v27, 0, v30
	v_add_f32_e32 v16, 0, v16
	v_add_f32_e32 v17, 0, v17
	v_add_f32_e32 v28, 0, v31
	v_cvt_pk_bf16_f32 v27, v27, v28
	s_and_saveexec_b64 s[98:99], s[88:89]
	global_store_dwordx2 v[24:25], v[26:27], off offset:32
	s_mov_b64 exec, s[98:99]
	v_cvt_pk_bf16_f32 v16, v16, v17
	v_add_f32_e32 v17, 0, v18
	v_add_f32_e32 v8, 0, v8
	v_add_f32_e32 v9, 0, v9
	v_add_f32_e32 v18, 0, v19
	v_cvt_pk_bf16_f32 v17, v17, v18
	s_and_saveexec_b64 s[98:99], s[88:89]
	global_store_dwordx2 v[24:25], v[16:17], off offset:256
	s_mov_b64 exec, s[98:99]
	v_cvt_pk_bf16_f32 v8, v8, v9
	v_add_f32_e32 v9, 0, v10
	v_add_f32_e32 v10, 0, v11
	v_cvt_pk_bf16_f32 v9, v9, v10
	v_add_f32_e32 v10, 0, v20
	v_add_f32_e32 v11, 0, v21
	s_and_saveexec_b64 s[98:99], s[88:89]
	global_store_dwordx2 v[24:25], v[8:9], off offset:288
	s_mov_b64 exec, s[98:99]
	v_cvt_pk_bf16_f32 v10, v10, v11
	v_add_f32_e32 v11, 0, v22
	v_add_f32_e32 v16, 0, v23
	v_cvt_pk_bf16_f32 v11, v11, v16
	v_add_co_u32_e32 v16, vcc, s72, v140
	v_lshl_add_u64 v[8:9], v[140:141], 0, s[42:43]
	s_nop 0
	v_addc_co_u32_e32 v17, vcc, 0, v141, vcc
	s_and_saveexec_b64 s[98:99], s[88:89]
	global_store_dwordx2 v[16:17], v[10:11], off
	s_mov_b64 exec, s[98:99]
	v_add_f32_e32 v10, 0, v12
	v_add_f32_e32 v11, 0, v13
	v_cvt_pk_bf16_f32 v10, v10, v11
	v_add_f32_e32 v11, 0, v14
	v_add_f32_e32 v4, 0, v4
	v_add_f32_e32 v5, 0, v5
	v_add_f32_e32 v12, 0, v15
	v_cvt_pk_bf16_f32 v11, v11, v12
	s_and_saveexec_b64 s[98:99], s[88:89]
	global_store_dwordx2 v[8:9], v[10:11], off offset:32
	s_mov_b64 exec, s[98:99]
	v_cvt_pk_bf16_f32 v4, v4, v5
	v_add_f32_e32 v5, 0, v6
	v_add_f32_e32 v0, 0, v0
	v_add_f32_e32 v1, 0, v1
	v_add_f32_e32 v6, 0, v7
	v_cvt_pk_bf16_f32 v5, v5, v6
	s_and_saveexec_b64 s[98:99], s[88:89]
	global_store_dwordx2 v[8:9], v[4:5], off offset:256
	s_mov_b64 exec, s[98:99]
	v_cvt_pk_bf16_f32 v0, v0, v1
	v_add_f32_e32 v1, 0, v2
	v_add_f32_e32 v2, 0, v3
	v_cvt_pk_bf16_f32 v1, v1, v2
	s_and_saveexec_b64 s[98:99], s[88:89]
	global_store_dwordx2 v[8:9], v[0:1], off offset:288
	s_mov_b64 exec, s[98:99]
	s_and_b64 vcc, exec, s[4:5]
	s_mov_b32 s74, s73
	v_mov_b32_e32 v140, v142
	v_mov_b64_e32 v[0:1], v[144:145]
	v_mov_b64_e32 v[2:3], v[146:147]
	s_mov_b32 s90, s91
	s_bitcmp1_b32 s90, 0
	s_cselect_b64 s[86:87], -1, 0
	s_bitcmp1_b32 s90, 1
	s_cselect_b64 s[88:89], -1, 0
	s_cbranch_vccz .LBB0_1821
	s_branch .Lts_b_after
.Lts_b_sel:
	s_cmp_eq_u32 s90, 1
	s_cbranch_scc0 .Lts_b_h1

.Lts_b_after:
	s_waitcnt vmcnt(0)
	s_cmpk_gt_u32 s46, 0xff
	s_cbranch_scc1 .LBB0_1836
	s_barrier
